# fin2 + spatial: W_g tile loads issued together with v/g/b loads (alignment-preserving pad)
# speedup vs baseline: 1.0121x; 1.0005x over previous
.LBB0_182:
	v_lshl_add_u64 v[12:13], s[26:27], 0, v[78:79]
	s_waitcnt lgkmcnt(0)
	s_barrier
	global_load_dwordx4 v[200:203], v[12:13], off offset:16
	global_load_dwordx4 v[204:207], v[12:13], off
	global_load_dwordx4 v[208:211], v[12:13], off offset:-16
	global_load_dwordx4 v[212:215], v[12:13], off offset:-32
	s_mov_b64 s[0:1], 0xa1d0800
	v_lshl_add_u64 v[16:17], v[36:37], 0, s[6:7]
	v_lshl_add_u64 v[0:1], s[26:27], 0, v[60:61]
	v_lshl_add_u64 v[10:11], v[0:1], 0, s[0:1]
	s_mov_b32 s0, 0xa1d0000
	v_add_co_u32_e64 v0, s[40:41], s0, v0
	v_lshl_add_u64 v[4:5], v[34:35], 0, s[6:7]
	s_nop 0
	v_addc_co_u32_e64 v1, s[40:41], 0, v1, s[40:41]
	ds_read_b32 v19, v85
	ds_read_b32 v18, v86
	global_load_dwordx4 v[6:9], v[0:1], off offset:2048
	s_nop 0
	global_load_dwordx4 v[0:3], v[10:11], off offset:48
	global_load_dwordx4 v[12:15], v[10:11], off offset:32
	global_load_dwordx4 v[20:23], v[10:11], off offset:16
	global_load_dwordx4 v[24:27], v[4:5], off offset:48
	global_load_dwordx4 v[28:31], v[4:5], off offset:32
	global_load_dwordx4 v[80:83], v[4:5], off offset:16
	global_load_dwordx4 v[118:121], v[4:5], off
	global_load_dwordx4 v[122:125], v[16:17], off offset:48
	global_load_dwordx4 v[126:129], v[16:17], off offset:32
	global_load_dwordx4 v[130:133], v[16:17], off offset:16
	global_load_dwordx4 v[134:137], v[16:17], off
	v_lshl_add_u64 v[60:61], v[60:61], 0, s[66:67]
	s_waitcnt vmcnt(12)
	ds_write_b128 v84, v[212:215]
	ds_write_b128 v84, v[208:211] offset:16
	ds_write_b128 v84, v[204:207] offset:32
	ds_write_b128 v84, v[200:203] offset:48
	s_waitcnt vmcnt(11)
	v_lshlrev_b32_e32 v10, 16, v6
	v_and_b32_e32 v6, 0xffff0000, v6
	s_waitcnt lgkmcnt(5)
	v_sub_f32_e32 v10, v10, v19
	v_sub_f32_e32 v6, v6, v19
	s_waitcnt lgkmcnt(4)
	v_mul_f32_e32 v10, v18, v10
	v_mul_f32_e32 v6, v18, v6
	s_waitcnt vmcnt(0)
	v_fma_f32 v10, v118, v10, v134
	v_fma_f32 v6, v119, v6, v135
	v_cvt_pk_bf16_f32 v10, v10, s0
	v_cvt_pk_bf16_f32 v6, v6, s0
	ds_write_b16 v87, v10 offset:34816
	ds_write_b16 v88, v6 offset:34816
	v_lshlrev_b32_e32 v6, 16, v7
	v_sub_f32_e32 v6, v6, v19
	v_and_b32_e32 v7, 0xffff0000, v7
	v_mul_f32_e32 v6, v18, v6
	v_sub_f32_e32 v7, v7, v19
	v_fma_f32 v6, v6, v120, v136
	v_mul_f32_e32 v7, v18, v7
	v_fmac_f32_e32 v137, v7, v121
	v_cvt_pk_bf16_f32 v6, v6, s0
	ds_write_b16 v89, v6 offset:34816
	v_cvt_pk_bf16_f32 v6, v137, s0
	ds_write_b16 v90, v6 offset:34816
	v_lshlrev_b32_e32 v6, 16, v8
	v_sub_f32_e32 v6, v6, v19
	v_and_b32_e32 v7, 0xffff0000, v8
	v_mul_f32_e32 v6, v18, v6
	v_sub_f32_e32 v7, v7, v19
	v_fma_f32 v6, v6, v80, v130
	v_mul_f32_e32 v7, v18, v7
	v_fma_f32 v7, v7, v81, v131
	v_cvt_pk_bf16_f32 v6, v6, s0
	ds_write_b16 v91, v6 offset:34816
	v_cvt_pk_bf16_f32 v6, v7, s0
	ds_write_b16 v92, v6 offset:34816
	v_lshlrev_b32_e32 v6, 16, v9
	v_sub_f32_e32 v6, v6, v19
	v_and_b32_e32 v7, 0xffff0000, v9
	v_mul_f32_e32 v6, v18, v6
	v_sub_f32_e32 v7, v7, v19
	v_fma_f32 v6, v6, v82, v132
	v_mul_f32_e32 v7, v18, v7
	v_fmac_f32_e32 v133, v7, v83
	v_cvt_pk_bf16_f32 v6, v6, s0
	ds_write_b16 v93, v6 offset:34816
	v_cvt_pk_bf16_f32 v6, v133, s0
	ds_write_b16 v94, v6 offset:34816
	v_lshlrev_b32_e32 v6, 16, v20
	v_sub_f32_e32 v6, v6, v19
	v_and_b32_e32 v7, 0xffff0000, v20
	v_mul_f32_e32 v6, v18, v6
	v_sub_f32_e32 v7, v7, v19
	v_fma_f32 v6, v28, v6, v126
	v_mul_f32_e32 v7, v18, v7
	v_fma_f32 v7, v29, v7, v127
	v_cvt_pk_bf16_f32 v6, v6, s0
	ds_write_b16 v87, v6 offset:35088
	v_cvt_pk_bf16_f32 v6, v7, s0
	ds_write_b16 v95, v6 offset:34816
	v_lshlrev_b32_e32 v6, 16, v21
	v_sub_f32_e32 v6, v6, v19
	v_and_b32_e32 v7, 0xffff0000, v21
	v_mul_f32_e32 v6, v18, v6
	v_sub_f32_e32 v7, v7, v19
	v_fma_f32 v6, v6, v30, v128
	v_mul_f32_e32 v7, v18, v7
	v_fmac_f32_e32 v129, v7, v31
	v_cvt_pk_bf16_f32 v6, v6, s0
	ds_write_b16 v96, v6 offset:34816
	v_cvt_pk_bf16_f32 v6, v129, s0
	ds_write_b16 v97, v6 offset:34816
	v_lshlrev_b32_e32 v6, 16, v22
	v_sub_f32_e32 v6, v6, v19
	v_and_b32_e32 v7, 0xffff0000, v22
	v_mul_f32_e32 v6, v18, v6
	v_sub_f32_e32 v7, v7, v19
	v_fma_f32 v6, v6, v24, v122
	v_mul_f32_e32 v7, v18, v7
	v_fma_f32 v7, v7, v25, v123
	v_cvt_pk_bf16_f32 v6, v6, s0
	ds_write_b16 v98, v6 offset:34816
	v_cvt_pk_bf16_f32 v6, v7, s0
	ds_write_b16 v99, v6 offset:34816
	v_lshlrev_b32_e32 v6, 16, v23
	v_sub_f32_e32 v6, v6, v19
	v_and_b32_e32 v7, 0xffff0000, v23
	v_mul_f32_e32 v6, v18, v6
	v_sub_f32_e32 v7, v7, v19
	v_fma_f32 v6, v6, v26, v124
	v_mul_f32_e32 v7, v18, v7
	v_fmac_f32_e32 v125, v7, v27
	v_cvt_pk_bf16_f32 v6, v6, s0
	ds_write_b16 v100, v6 offset:34816
	v_cvt_pk_bf16_f32 v6, v125, s0
	ds_write_b16 v101, v6 offset:34816
	v_lshlrev_b32_e32 v6, 16, v12
	v_sub_f32_e32 v6, v6, v19
	v_mul_f32_e32 v41, v18, v6
	global_load_dwordx4 v[8:11], v[4:5], off offset:112
	global_load_dwordx4 v[20:23], v[4:5], off offset:96
	global_load_dwordx4 v[24:27], v[4:5], off offset:80
	global_load_dwordx4 v[28:31], v[4:5], off offset:64
	s_nop 0
	global_load_dwordx4 v[4:7], v[16:17], off offset:112
	global_load_dwordx4 v[80:83], v[16:17], off offset:96
	global_load_dwordx4 v[118:121], v[16:17], off offset:80
	global_load_dwordx4 v[122:125], v[16:17], off offset:64
	v_and_b32_e32 v12, 0xffff0000, v12
	v_sub_f32_e32 v12, v12, v19
	v_mul_f32_e32 v12, v18, v12
	s_waitcnt vmcnt(0)
	v_fma_f32 v16, v28, v41, v122
	v_fma_f32 v12, v29, v12, v123
	v_cvt_pk_bf16_f32 v16, v16, s0
	v_cvt_pk_bf16_f32 v12, v12, s0
	ds_write_b16 v87, v16 offset:35360
	ds_write_b16 v102, v12 offset:34816
	v_lshlrev_b32_e32 v12, 16, v13
	v_sub_f32_e32 v12, v12, v19
	v_and_b32_e32 v13, 0xffff0000, v13
	v_mul_f32_e32 v12, v18, v12
	v_sub_f32_e32 v13, v13, v19
	v_fma_f32 v12, v12, v30, v124
	v_mul_f32_e32 v13, v18, v13
	v_fmac_f32_e32 v125, v13, v31
	v_cvt_pk_bf16_f32 v12, v12, s0
	ds_write_b16 v103, v12 offset:34816
	v_cvt_pk_bf16_f32 v12, v125, s0
	ds_write_b16 v104, v12 offset:34816
	v_lshlrev_b32_e32 v12, 16, v14
	v_sub_f32_e32 v12, v12, v19
	v_and_b32_e32 v13, 0xffff0000, v14
	v_mul_f32_e32 v12, v18, v12
	v_sub_f32_e32 v13, v13, v19
	v_fma_f32 v12, v12, v24, v118
	v_mul_f32_e32 v13, v18, v13
	v_fma_f32 v13, v13, v25, v119
	v_cvt_pk_bf16_f32 v12, v12, s0
	ds_write_b16 v105, v12 offset:34816
	v_cvt_pk_bf16_f32 v12, v13, s0
	ds_write_b16 v106, v12 offset:34816
	v_lshlrev_b32_e32 v12, 16, v15
	v_sub_f32_e32 v12, v12, v19
	v_and_b32_e32 v13, 0xffff0000, v15
	v_mul_f32_e32 v12, v18, v12
	v_sub_f32_e32 v13, v13, v19
	v_fma_f32 v12, v12, v26, v120
	v_mul_f32_e32 v13, v18, v13
	v_fmac_f32_e32 v121, v13, v27
	v_cvt_pk_bf16_f32 v12, v12, s0
	ds_write_b16 v107, v12 offset:34816
	v_cvt_pk_bf16_f32 v12, v121, s0
	ds_write_b16 v108, v12 offset:34816
	v_lshlrev_b32_e32 v12, 16, v0
	v_and_b32_e32 v0, 0xffff0000, v0
	v_sub_f32_e32 v12, v12, v19
	v_sub_f32_e32 v0, v0, v19
	v_mul_f32_e32 v12, v18, v12
	v_mul_f32_e32 v0, v18, v0
	v_fma_f32 v12, v20, v12, v80
	v_fma_f32 v0, v21, v0, v81
	v_cvt_pk_bf16_f32 v12, v12, s0
	v_cvt_pk_bf16_f32 v0, v0, s0
	ds_write_b16 v109, v12 offset:34816
	ds_write_b16 v110, v0 offset:34816
	v_lshlrev_b32_e32 v0, 16, v1
	v_sub_f32_e32 v0, v0, v19
	v_and_b32_e32 v1, 0xffff0000, v1
	v_mul_f32_e32 v0, v18, v0
	v_sub_f32_e32 v1, v1, v19
	v_fma_f32 v0, v0, v22, v82
	v_mul_f32_e32 v1, v18, v1
	v_fmac_f32_e32 v83, v1, v23
	v_cvt_pk_bf16_f32 v0, v0, s0
	ds_write_b16 v111, v0 offset:34816
	v_cvt_pk_bf16_f32 v0, v83, s0
	ds_write_b16 v112, v0 offset:34816
	v_lshlrev_b32_e32 v0, 16, v2
	v_sub_f32_e32 v0, v0, v19
	v_and_b32_e32 v1, 0xffff0000, v2
	v_mul_f32_e32 v0, v18, v0
	v_sub_f32_e32 v1, v1, v19
	v_fma_f32 v0, v0, v8, v4
	v_mul_f32_e32 v1, v18, v1
	v_fma_f32 v1, v1, v9, v5
	v_cvt_pk_bf16_f32 v0, v0, s0
	ds_write_b16 v113, v0 offset:34816
	v_cvt_pk_bf16_f32 v0, v1, s0
	ds_write_b16 v114, v0 offset:34816
	v_lshlrev_b32_e32 v0, 16, v3
	v_sub_f32_e32 v0, v0, v19
	v_and_b32_e32 v1, 0xffff0000, v3
	v_mul_f32_e32 v0, v18, v0
	v_sub_f32_e32 v1, v1, v19
	v_fma_f32 v0, v0, v10, v6
	v_mul_f32_e32 v1, v18, v1
	v_fmac_f32_e32 v7, v1, v11
	v_cvt_pk_bf16_f32 v0, v0, s0
	ds_write_b16 v115, v0 offset:34816
	v_cvt_pk_bf16_f32 v0, v7, s0
	ds_write_b16 v116, v0 offset:34816
	s_waitcnt lgkmcnt(0)
	s_barrier
	ds_read_b128 v[0:3], v32
	ds_read_b128 v[4:7], v117 offset:34816
	ds_read_b128 v[8:11], v117 offset:39168
	ds_read_b128 v[12:15], v117 offset:43520
	ds_read_b128 v[16:19], v117 offset:47872
	ds_read_b128 v[20:23], v117 offset:52224
	ds_read_b128 v[24:27], v117 offset:56576
	ds_read_b128 v[28:31], v117 offset:60928
	ds_read_b128 v[80:83], v117 offset:65280
	s_waitcnt lgkmcnt(7)
	v_mfma_f32_16x16x32_bf16 v[4:7], v[0:3], v[4:7], 0
	s_mov_b64 s[0:1], 0x8000
	v_lshl_add_u64 v[78:79], v[78:79], 0, s[0:1]
	s_waitcnt lgkmcnt(6)
	v_mfma_f32_16x16x32_bf16 v[8:11], v[0:3], v[8:11], 0
	s_waitcnt lgkmcnt(5)
	v_mfma_f32_16x16x32_bf16 v[12:15], v[0:3], v[12:15], 0
	s_waitcnt lgkmcnt(4)
	v_mfma_f32_16x16x32_bf16 v[16:19], v[0:3], v[16:19], 0
	s_waitcnt lgkmcnt(3)
	v_mfma_f32_16x16x32_bf16 v[20:23], v[0:3], v[20:23], 0
	s_waitcnt lgkmcnt(2)
	v_mfma_f32_16x16x32_bf16 v[24:27], v[0:3], v[24:27], 0
	s_waitcnt lgkmcnt(1)
	v_mfma_f32_16x16x32_bf16 v[28:31], v[0:3], v[28:31], 0
	s_waitcnt lgkmcnt(0)
	v_mfma_f32_16x16x32_bf16 v[0:3], v[0:3], v[80:83], 0
	ds_read_b128 v[80:83], v32 offset:64
	ds_read_b128 v[118:121], v117 offset:34880
	s_waitcnt lgkmcnt(0)
	v_mfma_f32_16x16x32_bf16 v[4:7], v[80:83], v[118:121], v[4:7]
	ds_read_b128 v[118:121], v117 offset:39232
	s_waitcnt lgkmcnt(0)
	v_mfma_f32_16x16x32_bf16 v[8:11], v[80:83], v[118:121], v[8:11]
	ds_read_b128 v[118:121], v117 offset:43584
	s_waitcnt lgkmcnt(0)
	v_mfma_f32_16x16x32_bf16 v[12:15], v[80:83], v[118:121], v[12:15]
	ds_read_b128 v[118:121], v117 offset:47936
	s_waitcnt lgkmcnt(0)
	v_mfma_f32_16x16x32_bf16 v[16:19], v[80:83], v[118:121], v[16:19]
	ds_read_b128 v[118:121], v117 offset:52288
	s_waitcnt lgkmcnt(0)
	v_mfma_f32_16x16x32_bf16 v[20:23], v[80:83], v[118:121], v[20:23]
	ds_read_b128 v[118:121], v117 offset:56640
	s_waitcnt lgkmcnt(0)
	v_mfma_f32_16x16x32_bf16 v[24:27], v[80:83], v[118:121], v[24:27]
	ds_read_b128 v[118:121], v117 offset:60992
	s_waitcnt lgkmcnt(0)
	v_mfma_f32_16x16x32_bf16 v[28:31], v[80:83], v[118:121], v[28:31]
	ds_read_b128 v[118:121], v117 offset:65344
	s_waitcnt lgkmcnt(0)
	v_mfma_f32_16x16x32_bf16 v[0:3], v[80:83], v[118:121], v[0:3]
	ds_read_b128 v[80:83], v32 offset:128
	ds_read_b128 v[118:121], v117 offset:34944
	s_waitcnt lgkmcnt(0)
	v_mfma_f32_16x16x32_bf16 v[4:7], v[80:83], v[118:121], v[4:7]
	ds_read_b128 v[118:121], v117 offset:39296
	s_waitcnt lgkmcnt(0)
	v_mfma_f32_16x16x32_bf16 v[8:11], v[80:83], v[118:121], v[8:11]
	ds_read_b128 v[118:121], v117 offset:43648
	s_waitcnt lgkmcnt(0)
	v_mfma_f32_16x16x32_bf16 v[12:15], v[80:83], v[118:121], v[12:15]
	ds_read_b128 v[118:121], v117 offset:48000
	s_waitcnt lgkmcnt(0)
	v_mfma_f32_16x16x32_bf16 v[16:19], v[80:83], v[118:121], v[16:19]
	ds_read_b128 v[118:121], v117 offset:52352
	s_waitcnt lgkmcnt(0)
	v_mfma_f32_16x16x32_bf16 v[20:23], v[80:83], v[118:121], v[20:23]
	ds_read_b128 v[118:121], v117 offset:56704
	s_waitcnt lgkmcnt(0)
	v_mfma_f32_16x16x32_bf16 v[24:27], v[80:83], v[118:121], v[24:27]
	ds_read_b128 v[118:121], v117 offset:61056
	s_waitcnt lgkmcnt(0)
	v_mfma_f32_16x16x32_bf16 v[28:31], v[80:83], v[118:121], v[28:31]
	ds_read_b128 v[118:121], v117 offset:65408
	s_waitcnt lgkmcnt(0)
	v_mfma_f32_16x16x32_bf16 v[80:83], v[80:83], v[118:121], v[0:3]
	ds_read_b128 v[118:121], v32 offset:192
	s_nop 1
	ds_read_b128 v[0:3], v117 offset:35008
	s_waitcnt lgkmcnt(0)
	v_mfma_f32_16x16x32_bf16 v[0:3], v[118:121], v[0:3], v[4:7]
	s_nop 2
	ds_read_b128 v[4:7], v117 offset:39360
	s_waitcnt lgkmcnt(0)
	v_mfma_f32_16x16x32_bf16 v[4:7], v[118:121], v[4:7], v[8:11]
	s_nop 2
	ds_read_b128 v[8:11], v117 offset:43712
	s_waitcnt lgkmcnt(0)
	v_mfma_f32_16x16x32_bf16 v[8:11], v[118:121], v[8:11], v[12:15]
	s_nop 2
	ds_read_b128 v[12:15], v117 offset:48064
	s_waitcnt lgkmcnt(0)
	v_mfma_f32_16x16x32_bf16 v[12:15], v[118:121], v[12:15], v[16:19]
	s_nop 2
	ds_read_b128 v[16:19], v117 offset:52416
	s_waitcnt lgkmcnt(0)
	v_mfma_f32_16x16x32_bf16 v[16:19], v[118:121], v[16:19], v[20:23]
	s_nop 2
	ds_read_b128 v[20:23], v117 offset:56768
	s_waitcnt lgkmcnt(0)
	v_mfma_f32_16x16x32_bf16 v[20:23], v[118:121], v[20:23], v[24:27]
	s_nop 2
	ds_read_b128 v[24:27], v117 offset:61120
	s_waitcnt lgkmcnt(0)
	v_mfma_f32_16x16x32_bf16 v[24:27], v[118:121], v[24:27], v[28:31]
	s_nop 2
	ds_read_b128 v[28:31], v117 offset:65472
	s_waitcnt lgkmcnt(0)
	v_mfma_f32_16x16x32_bf16 v[28:31], v[118:121], v[28:31], v[80:83]
	s_nop 2
	v_lshl_add_u64 v[80:81], v[44:45], 0, s[6:7]
	v_lshl_add_u64 v[82:83], s[26:27], 0, v[66:67]
	global_load_dword v41, v[80:81], off
	global_load_dwordx4 v[118:121], v[82:83], off
	v_lshl_add_u64 v[82:83], s[26:27], 0, v[74:75]
	s_add_u32 s6, s6, 0x200
	s_addc_u32 s7, s7, 0
	v_lshl_add_u64 v[66:67], v[66:67], 0, s[66:67]
	v_lshl_add_u64 v[74:75], v[74:75], 0, s[66:67]
	s_cmpk_eq_i32 s6, 0x1000
	s_waitcnt vmcnt(1)
	v_add_f32_e32 v0, v0, v41
	s_waitcnt vmcnt(0)
	v_lshlrev_b32_e32 v49, 16, v118
	v_mul_f32_e32 v0, v0, v49
	v_and_b32_e32 v49, 0xffff0000, v118
	v_add_f32_e32 v4, v4, v41
	v_mul_f32_e32 v4, v4, v49
	v_cvt_pk_bf16_f32 v118, v0, v4
	v_lshlrev_b32_e32 v0, 16, v119
	v_add_f32_e32 v4, v8, v41
	v_mul_f32_e32 v0, v4, v0
	v_and_b32_e32 v4, 0xffff0000, v119
	v_add_f32_e32 v8, v12, v41
	v_mul_f32_e32 v4, v8, v4
	v_cvt_pk_bf16_f32 v119, v0, v4
	v_lshlrev_b32_e32 v0, 16, v120
	v_add_f32_e32 v4, v16, v41
	v_mul_f32_e32 v0, v4, v0
	v_and_b32_e32 v4, 0xffff0000, v120
	v_add_f32_e32 v8, v20, v41
	v_mul_f32_e32 v4, v8, v4
	v_cvt_pk_bf16_f32 v120, v0, v4
	v_lshlrev_b32_e32 v0, 16, v121
	v_add_f32_e32 v4, v24, v41
	v_mul_f32_e32 v0, v4, v0
	v_and_b32_e32 v4, 0xffff0000, v121
	v_add_f32_e32 v8, v28, v41
	v_mul_f32_e32 v4, v8, v4
	v_cvt_pk_bf16_f32 v121, v0, v4
	global_store_dwordx4 v[82:83], v[118:121], off
	v_lshl_add_u64 v[82:83], s[26:27], 0, v[68:69]
	global_load_dword v0, v[80:81], off offset:4
	global_load_dwordx4 v[118:121], v[82:83], off
	v_lshl_add_u64 v[68:69], v[68:69], 0, s[66:67]
	s_waitcnt vmcnt(1)
	v_add_f32_e32 v1, v1, v0
	s_waitcnt vmcnt(0)
	v_lshlrev_b32_e32 v4, 16, v118
	v_mul_f32_e32 v1, v1, v4
	v_and_b32_e32 v4, 0xffff0000, v118
	v_add_f32_e32 v5, v5, v0
	v_mul_f32_e32 v4, v5, v4
	v_cvt_pk_bf16_f32 v118, v1, v4
	v_lshlrev_b32_e32 v1, 16, v119
	v_add_f32_e32 v4, v9, v0
	v_mul_f32_e32 v1, v4, v1
	v_and_b32_e32 v4, 0xffff0000, v119
	v_add_f32_e32 v5, v13, v0
	v_mul_f32_e32 v4, v5, v4
	v_cvt_pk_bf16_f32 v119, v1, v4
	v_lshlrev_b32_e32 v1, 16, v120
	v_add_f32_e32 v4, v17, v0
	v_mul_f32_e32 v1, v4, v1
	v_and_b32_e32 v4, 0xffff0000, v120
	v_add_f32_e32 v5, v21, v0
	v_mul_f32_e32 v4, v5, v4
	v_cvt_pk_bf16_f32 v120, v1, v4
	v_lshlrev_b32_e32 v1, 16, v121
	v_add_f32_e32 v4, v25, v0
	v_mul_f32_e32 v1, v4, v1
	v_and_b32_e32 v4, 0xffff0000, v121
	v_add_f32_e32 v0, v29, v0
	v_mul_f32_e32 v0, v0, v4
	v_cvt_pk_bf16_f32 v121, v1, v0
	v_lshl_add_u64 v[0:1], s[26:27], 0, v[76:77]
	global_store_dwordx4 v[0:1], v[118:121], off
	v_lshl_add_u64 v[0:1], s[26:27], 0, v[70:71]
	global_load_dword v4, v[80:81], off offset:8
	global_load_dwordx4 v[118:121], v[0:1], off
	v_lshl_add_u64 v[70:71], v[70:71], 0, s[66:67]
	v_lshl_add_u64 v[76:77], v[76:77], 0, s[66:67]
	s_waitcnt vmcnt(1)
	v_add_f32_e32 v1, v2, v4
	s_waitcnt vmcnt(0)
	v_lshlrev_b32_e32 v0, 16, v118
	v_mul_f32_e32 v0, v1, v0
	v_and_b32_e32 v1, 0xffff0000, v118
	v_add_f32_e32 v2, v6, v4
	v_mul_f32_e32 v1, v2, v1
	v_cvt_pk_bf16_f32 v118, v0, v1
	v_lshlrev_b32_e32 v0, 16, v119
	v_add_f32_e32 v1, v10, v4
	v_mul_f32_e32 v0, v1, v0
	v_and_b32_e32 v1, 0xffff0000, v119
	v_add_f32_e32 v2, v14, v4
	v_mul_f32_e32 v1, v2, v1
	v_cvt_pk_bf16_f32 v119, v0, v1
	v_lshlrev_b32_e32 v0, 16, v120
	v_add_f32_e32 v1, v18, v4
	v_mul_f32_e32 v0, v1, v0
	v_and_b32_e32 v1, 0xffff0000, v120
	v_add_f32_e32 v2, v22, v4
	v_mul_f32_e32 v1, v2, v1
	v_cvt_pk_bf16_f32 v120, v0, v1
	v_lshlrev_b32_e32 v0, 16, v121
	v_add_f32_e32 v1, v26, v4
	v_mul_f32_e32 v0, v1, v0
	v_and_b32_e32 v1, 0xffff0000, v121
	v_add_f32_e32 v2, v30, v4
	v_mul_f32_e32 v1, v2, v1
	v_cvt_pk_bf16_f32 v121, v0, v1
	v_lshl_add_u64 v[0:1], s[26:27], 0, v[64:65]
	global_store_dwordx4 v[0:1], v[118:121], off
	v_lshl_add_u64 v[0:1], s[26:27], 0, v[72:73]
	global_load_dword v4, v[80:81], off offset:12
	v_lshl_add_u64 v[64:65], v[64:65], 0, s[66:67]
	global_load_dwordx4 v[80:83], v[0:1], off
	v_lshl_add_u64 v[72:73], v[72:73], 0, s[66:67]
	s_waitcnt vmcnt(1)
	v_add_f32_e32 v1, v3, v4
	v_add_f32_e32 v2, v7, v4
	s_waitcnt vmcnt(0)
	v_lshlrev_b32_e32 v0, 16, v80
	v_mul_f32_e32 v0, v1, v0
	v_and_b32_e32 v1, 0xffff0000, v80
	v_mul_f32_e32 v1, v2, v1
	v_cvt_pk_bf16_f32 v0, v0, v1
	v_lshlrev_b32_e32 v1, 16, v81
	v_add_f32_e32 v2, v11, v4
	v_mul_f32_e32 v1, v2, v1
	v_and_b32_e32 v2, 0xffff0000, v81
	v_add_f32_e32 v3, v15, v4
	v_mul_f32_e32 v2, v3, v2
	v_cvt_pk_bf16_f32 v1, v1, v2
	v_lshlrev_b32_e32 v2, 16, v82
	v_add_f32_e32 v3, v19, v4
	v_mul_f32_e32 v2, v3, v2
	v_and_b32_e32 v3, 0xffff0000, v82
	v_add_f32_e32 v5, v23, v4
	v_mul_f32_e32 v3, v5, v3
	v_cvt_pk_bf16_f32 v2, v2, v3
	v_lshlrev_b32_e32 v3, 16, v83
	v_add_f32_e32 v5, v27, v4
	v_mul_f32_e32 v3, v5, v3
	v_and_b32_e32 v5, 0xffff0000, v83
	v_add_f32_e32 v4, v31, v4
	v_mul_f32_e32 v4, v4, v5
	v_cvt_pk_bf16_f32 v3, v3, v4
	v_lshl_add_u64 v[4:5], s[26:27], 0, v[62:63]
	v_lshl_add_u64 v[62:63], v[62:63], 0, s[66:67]
	global_store_dwordx4 v[4:5], v[0:3], off
	s_cbranch_scc0 .LBB0_182
	s_add_i32 s8, s8, s62
	v_add_u32_e32 v40, s3, v40
	v_add_u32_e32 v48, s3, v48
	v_add_u32_e32 v50, s3, v50
	v_add_u32_e32 v52, s3, v52
	v_add_u32_e32 v56, s3, v56
	s_cmp_ge_i32 s8, s5
	v_add_u32_e32 v58, s3, v58
	s_barrier
	s_cbranch_scc0 .LBB0_177
	v_readlane_b32 s76, v250, 16
	v_readlane_b32 s68, v250, 23
	v_readlane_b32 s70, v250, 25
	v_readlane_b32 s80, v250, 27
	v_readlane_b32 s78, v250, 15
	v_readlane_b32 s77, v250, 17
	v_readlane_b32 s74, v250, 18
	v_readlane_b32 s73, v250, 21
	v_readlane_b32 s65, v250, 22
	v_readlane_b32 s69, v250, 24
	v_readlane_b32 s71, v250, 26
	v_readlane_b32 s81, v250, 28
	s_mov_b32 s75, 0x11000
	s_movk_i32 s79, 0x60
	s_movk_i32 s64, 0x1000
	s_mov_b32 s72, 0x3f07dc22

.Lfin2_check:
	v_add_u32_e32 v72, s74, v0
	v_cmp_gt_i32_e32 vcc, s0, v72
	s_nop 4
	s_cbranch_vccz .LBB0_189
	v_ashrrev_i32_e32 v1, 31, v0
	v_lshlrev_b64 v[24:25], 12, v[0:1]
	v_lshl_add_u64 v[36:37], v[2:3], 0, v[24:25]
	global_load_dwordx4 v[24:27], v[36:37], off offset:16
	global_load_dwordx4 v[28:31], v[36:37], off
	global_load_dwordx4 v[32:35], v[36:37], off offset:272
	global_load_dwordx4 v[36:39], v[36:37], off offset:256
	v_ashrrev_i32_e32 v73, 31, v72
	v_lshlrev_b64 v[50:51], 12, v[72:73]
	v_lshl_add_u64 v[62:63], v[2:3], 0, v[50:51]
	global_load_dwordx4 v[50:53], v[62:63], off offset:16
	global_load_dwordx4 v[54:57], v[62:63], off
	global_load_dwordx4 v[58:61], v[62:63], off offset:272
	global_load_dwordx4 v[62:65], v[62:63], off offset:256
	s_waitcnt vmcnt(6)
	v_lshlrev_b32_e32 v40, 16, v28
	v_and_b32_e32 v28, 0xffff0000, v28
	s_waitcnt vmcnt(4)
	v_lshlrev_b32_e32 v41, 16, v36
	v_and_b32_e32 v36, 0xffff0000, v36
	v_fma_f32 v40, -v6, v41, v40
	v_fma_f32 v36, -v6, v36, v28
	v_lshlrev_b32_e32 v28, 16, v29
	v_lshlrev_b32_e32 v41, 16, v37
	v_fma_f32 v41, -v6, v41, v28
	v_and_b32_e32 v28, 0xffff0000, v29
	v_and_b32_e32 v29, 0xffff0000, v37
	v_mul_f32_e32 v44, v36, v36
	v_fma_f32 v37, -v6, v29, v28
	v_lshlrev_b32_e32 v28, 16, v30
	v_lshlrev_b32_e32 v29, 16, v38
	v_fmac_f32_e32 v44, v40, v40
	v_fma_f32 v42, -v6, v29, v28
	v_and_b32_e32 v28, 0xffff0000, v30
	v_and_b32_e32 v29, 0xffff0000, v38
	v_fmac_f32_e32 v44, v41, v41
	v_fma_f32 v38, -v6, v29, v28
	v_lshlrev_b32_e32 v28, 16, v31
	v_lshlrev_b32_e32 v29, 16, v39
	v_fmac_f32_e32 v44, v37, v37
	v_fma_f32 v43, -v6, v29, v28
	v_and_b32_e32 v28, 0xffff0000, v31
	v_and_b32_e32 v29, 0xffff0000, v39
	v_fmac_f32_e32 v44, v42, v42
	v_fma_f32 v39, -v6, v29, v28
	v_fmac_f32_e32 v44, v38, v38
	v_and_b32_e32 v28, 0xffff0000, v24
	v_lshlrev_b32_e32 v29, 16, v24
	v_and_b32_e32 v30, 0xffff0000, v32
	v_lshlrev_b32_e32 v31, 16, v32
	v_fmac_f32_e32 v44, v43, v43
	v_pk_fma_f32 v[28:29], v[6:7], v[30:31], v[28:29] neg_lo:[1,0,0] neg_hi:[1,0,0]
	v_fmac_f32_e32 v44, v39, v39
	v_pk_mul_f32 v[30:31], v[28:29], v[28:29]
	s_nop 0
	v_add_f32_e32 v24, v31, v44
	v_add_f32_e32 v32, v30, v24
	v_and_b32_e32 v24, 0xffff0000, v25
	v_lshlrev_b32_e32 v25, 16, v25
	v_and_b32_e32 v30, 0xffff0000, v33
	v_lshlrev_b32_e32 v31, 16, v33
	v_pk_fma_f32 v[30:31], v[6:7], v[30:31], v[24:25] neg_lo:[1,0,0] neg_hi:[1,0,0]
	v_lshlrev_b32_e32 v33, 16, v34
	v_pk_mul_f32 v[24:25], v[30:31], v[30:31]
	s_nop 0
	v_add_f32_e32 v25, v25, v32
	v_add_f32_e32 v44, v24, v25
	v_and_b32_e32 v24, 0xffff0000, v26
	v_lshlrev_b32_e32 v25, 16, v26
	v_and_b32_e32 v32, 0xffff0000, v34
	v_pk_fma_f32 v[32:33], v[6:7], v[32:33], v[24:25] neg_lo:[1,0,0] neg_hi:[1,0,0]
	v_and_b32_e32 v26, 0xffff0000, v35
	v_pk_mul_f32 v[24:25], v[32:33], v[32:33]
	s_nop 0
	v_add_f32_e32 v25, v25, v44
	v_add_f32_e32 v44, v24, v25
	v_and_b32_e32 v24, 0xffff0000, v27
	v_lshlrev_b32_e32 v25, 16, v27
	v_lshlrev_b32_e32 v27, 16, v35
	v_pk_fma_f32 v[34:35], v[6:7], v[26:27], v[24:25] neg_lo:[1,0,0] neg_hi:[1,0,0]
	s_nop 0
	v_pk_mul_f32 v[24:25], v[34:35], v[34:35]
	s_nop 0
	v_add_f32_e32 v25, v25, v44
	v_add_f32_e32 v24, v24, v25
	ds_swizzle_b32 v25, v24 offset:swizzle(SWAP,1)
	s_waitcnt lgkmcnt(0)
	v_add_f32_e32 v24, v24, v25
	ds_swizzle_b32 v25, v24 offset:swizzle(SWAP,2)
	s_waitcnt lgkmcnt(0)
	v_add_f32_e32 v24, v24, v25
	ds_swizzle_b32 v25, v24 offset:swizzle(SWAP,4)
	s_waitcnt lgkmcnt(0)
	v_add_f32_e32 v24, v24, v25
	v_fmamk_f32 v24, v24, 0x3c000000, v169
	v_cmp_gt_f32_e32 vcc, s85, v24
	v_mul_f32_e32 v25, 0x4b800000, v24
	s_nop 0
	v_cndmask_b32_e32 v24, v24, v25, vcc
	v_rsq_f32_e32 v24, v24
	s_nop 0
	v_mul_f32_e32 v25, 0x45800000, v24
	v_cndmask_b32_e32 v44, v24, v25, vcc
	v_mul_f32_e32 v24, v40, v44
	v_mul_f32_e32 v25, v36, v44
	v_mul_f32_e32 v24, v8, v24
	v_mul_f32_e32 v25, v9, v25
	v_cvt_pk_bf16_f32 v24, v24, v25
	v_mul_f32_e32 v25, v29, v44
	v_mul_f32_e32 v26, v28, v44
	v_mul_f32_e32 v25, v16, v25
	v_mul_f32_e32 v26, v17, v26
	v_cvt_pk_bf16_f32 v28, v25, v26
	v_mul_f32_e32 v25, v41, v44
	v_mul_f32_e32 v26, v37, v44
	v_mul_f32_e32 v25, v10, v25
	v_mul_f32_e32 v26, v11, v26
	v_cvt_pk_bf16_f32 v25, v25, v26
	v_mul_f32_e32 v26, v31, v44
	v_mul_f32_e32 v27, v30, v44
	v_mul_f32_e32 v26, v18, v26
	v_mul_f32_e32 v27, v19, v27
	v_cvt_pk_bf16_f32 v29, v26, v27
	v_mul_f32_e32 v26, v42, v44
	v_mul_f32_e32 v27, v38, v44
	v_mul_f32_e32 v26, v12, v26
	v_mul_f32_e32 v27, v13, v27
	v_cvt_pk_bf16_f32 v26, v26, v27
	v_mul_f32_e32 v27, v33, v44
	v_mul_f32_e32 v30, v32, v44
	v_mul_f32_e32 v27, v20, v27
	v_mul_f32_e32 v30, v21, v30
	v_cvt_pk_bf16_f32 v30, v27, v30
	v_mul_f32_e32 v27, v43, v44
	v_mul_f32_e32 v31, v39, v44
	v_mul_f32_e32 v27, v14, v27
	v_mul_f32_e32 v31, v15, v31
	v_cvt_pk_bf16_f32 v27, v27, v31
	v_mul_f32_e32 v31, v35, v44
	v_mul_f32_e32 v32, v34, v44
	v_mul_f32_e32 v31, v22, v31
	v_mul_f32_e32 v32, v23, v32
	v_cvt_pk_bf16_f32 v31, v31, v32
	v_lshlrev_b64 v[32:33], 11, v[0:1]
	v_lshl_add_u64 v[32:33], v[4:5], 0, v[32:33]
	s_waitcnt vmcnt(2)
	v_lshlrev_b32_e32 v66, 16, v54
	v_and_b32_e32 v54, 0xffff0000, v54
	s_waitcnt vmcnt(0)
	v_lshlrev_b32_e32 v67, 16, v62
	v_and_b32_e32 v62, 0xffff0000, v62
	v_fma_f32 v66, -v6, v67, v66
	v_fma_f32 v62, -v6, v62, v54
	v_lshlrev_b32_e32 v54, 16, v55
	v_lshlrev_b32_e32 v67, 16, v63
	v_fma_f32 v67, -v6, v67, v54
	v_and_b32_e32 v54, 0xffff0000, v55
	v_and_b32_e32 v55, 0xffff0000, v63
	v_mul_f32_e32 v70, v62, v62
	v_fma_f32 v63, -v6, v55, v54
	v_lshlrev_b32_e32 v54, 16, v56
	v_lshlrev_b32_e32 v55, 16, v64
	v_fmac_f32_e32 v70, v66, v66
	v_fma_f32 v68, -v6, v55, v54
	v_and_b32_e32 v54, 0xffff0000, v56
	v_and_b32_e32 v55, 0xffff0000, v64
	v_fmac_f32_e32 v70, v67, v67
	v_fma_f32 v64, -v6, v55, v54
	v_lshlrev_b32_e32 v54, 16, v57
	v_lshlrev_b32_e32 v55, 16, v65
	v_fmac_f32_e32 v70, v63, v63
	v_fma_f32 v69, -v6, v55, v54
	v_and_b32_e32 v54, 0xffff0000, v57
	v_and_b32_e32 v55, 0xffff0000, v65
	v_fmac_f32_e32 v70, v68, v68
	v_fma_f32 v65, -v6, v55, v54
	v_fmac_f32_e32 v70, v64, v64
	v_and_b32_e32 v54, 0xffff0000, v50
	v_lshlrev_b32_e32 v55, 16, v50
	v_and_b32_e32 v56, 0xffff0000, v58
	v_lshlrev_b32_e32 v57, 16, v58
	v_fmac_f32_e32 v70, v69, v69
	v_pk_fma_f32 v[54:55], v[6:7], v[56:57], v[54:55] neg_lo:[1,0,0] neg_hi:[1,0,0]
	v_fmac_f32_e32 v70, v65, v65
	v_pk_mul_f32 v[56:57], v[54:55], v[54:55]
	s_nop 0
	v_add_f32_e32 v50, v57, v70
	v_add_f32_e32 v58, v56, v50
	v_and_b32_e32 v50, 0xffff0000, v51
	v_lshlrev_b32_e32 v51, 16, v51
	v_and_b32_e32 v56, 0xffff0000, v59
	v_lshlrev_b32_e32 v57, 16, v59
	v_pk_fma_f32 v[56:57], v[6:7], v[56:57], v[50:51] neg_lo:[1,0,0] neg_hi:[1,0,0]
	v_lshlrev_b32_e32 v59, 16, v60
	v_pk_mul_f32 v[50:51], v[56:57], v[56:57]
	s_nop 0
	v_add_f32_e32 v51, v51, v58
	v_add_f32_e32 v70, v50, v51
	v_and_b32_e32 v50, 0xffff0000, v52
	v_lshlrev_b32_e32 v51, 16, v52
	v_and_b32_e32 v58, 0xffff0000, v60
	v_pk_fma_f32 v[58:59], v[6:7], v[58:59], v[50:51] neg_lo:[1,0,0] neg_hi:[1,0,0]
	v_and_b32_e32 v52, 0xffff0000, v61
	v_pk_mul_f32 v[50:51], v[58:59], v[58:59]
	s_nop 0
	v_add_f32_e32 v51, v51, v70
	v_add_f32_e32 v70, v50, v51
	v_and_b32_e32 v50, 0xffff0000, v53
	v_lshlrev_b32_e32 v51, 16, v53
	v_lshlrev_b32_e32 v53, 16, v61
	v_pk_fma_f32 v[60:61], v[6:7], v[52:53], v[50:51] neg_lo:[1,0,0] neg_hi:[1,0,0]
	s_nop 0
	v_pk_mul_f32 v[50:51], v[60:61], v[60:61]
	s_nop 0
	v_add_f32_e32 v51, v51, v70
	v_add_f32_e32 v50, v50, v51
	ds_swizzle_b32 v51, v50 offset:swizzle(SWAP,1)
	s_waitcnt lgkmcnt(0)
	v_add_f32_e32 v50, v50, v51
	ds_swizzle_b32 v51, v50 offset:swizzle(SWAP,2)
	s_waitcnt lgkmcnt(0)
	v_add_f32_e32 v50, v50, v51
	ds_swizzle_b32 v51, v50 offset:swizzle(SWAP,4)
	s_waitcnt lgkmcnt(0)
	v_add_f32_e32 v50, v50, v51
	v_fmamk_f32 v50, v50, 0x3c000000, v169
	v_cmp_gt_f32_e32 vcc, s85, v50
	v_mul_f32_e32 v51, 0x4b800000, v50
	s_nop 0
	v_cndmask_b32_e32 v50, v50, v51, vcc
	v_rsq_f32_e32 v50, v50
	s_nop 0
	v_mul_f32_e32 v51, 0x45800000, v50
	v_cndmask_b32_e32 v70, v50, v51, vcc
	v_mul_f32_e32 v50, v66, v70
	v_mul_f32_e32 v51, v62, v70
	v_mul_f32_e32 v50, v8, v50
	v_mul_f32_e32 v51, v9, v51
	v_cvt_pk_bf16_f32 v50, v50, v51
	v_mul_f32_e32 v51, v55, v70
	v_mul_f32_e32 v52, v54, v70
	v_mul_f32_e32 v51, v16, v51
	v_mul_f32_e32 v52, v17, v52
	v_cvt_pk_bf16_f32 v54, v51, v52
	v_mul_f32_e32 v51, v67, v70
	v_mul_f32_e32 v52, v63, v70
	v_mul_f32_e32 v51, v10, v51
	v_mul_f32_e32 v52, v11, v52
	v_cvt_pk_bf16_f32 v51, v51, v52
	v_mul_f32_e32 v52, v57, v70
	v_mul_f32_e32 v53, v56, v70
	v_mul_f32_e32 v52, v18, v52
	v_mul_f32_e32 v53, v19, v53
	v_cvt_pk_bf16_f32 v55, v52, v53
	v_mul_f32_e32 v52, v68, v70
	v_mul_f32_e32 v53, v64, v70
	v_mul_f32_e32 v52, v12, v52
	v_mul_f32_e32 v53, v13, v53
	v_cvt_pk_bf16_f32 v52, v52, v53
	v_mul_f32_e32 v53, v59, v70
	v_mul_f32_e32 v56, v58, v70
	v_mul_f32_e32 v53, v20, v53
	v_mul_f32_e32 v56, v21, v56
	v_cvt_pk_bf16_f32 v56, v53, v56
	v_mul_f32_e32 v53, v69, v70
	v_mul_f32_e32 v57, v65, v70
	v_mul_f32_e32 v53, v14, v53
	v_mul_f32_e32 v57, v15, v57
	v_cvt_pk_bf16_f32 v53, v53, v57
	v_mul_f32_e32 v57, v61, v70
	v_mul_f32_e32 v58, v60, v70
	v_mul_f32_e32 v57, v22, v57
	v_mul_f32_e32 v58, v23, v58
	v_cvt_pk_bf16_f32 v57, v57, v58
	v_lshlrev_b64 v[58:59], 11, v[72:73]
	v_lshl_add_u64 v[58:59], v[4:5], 0, v[58:59]
	global_store_dwordx4 v[58:59], v[50:53], off
	global_store_dwordx4 v[58:59], v[54:57], off offset:16
	global_store_dwordx4 v[32:33], v[24:27], off
	global_store_dwordx4 v[32:33], v[28:31], off offset:16
	v_add_u32_e32 v0, s74, v72
	v_cmp_gt_i32_e32 vcc, s0, v0
	s_nop 4
	s_cbranch_vccnz .Lfin2_check
	s_branch .LBB0_190
	s_nop 0
	s_nop 0
	s_nop 0
	s_nop 0
	s_nop 0
	s_nop 0
	s_nop 0
	s_nop 0
	s_nop 0
	s_nop 0
	s_nop 0
	s_nop 0
	s_nop 0
	s_nop 0
	s_nop 0
	s_nop 0
